# hyena PROMPT epilogue: 16 half-wave dwordx2 stores widened to 8 dwordx4 via v_permlane32_swap (same bytes, same addresses)
# baseline (speedup 1.0000x reference)
.Lpb_b:
	v_or_b32_e32 v64, s1, v137
	v_lshlrev_b32_e32 v65, 12, v138
	v_lshl_add_u32 v64, v64, 7, v65
	v_ashrrev_i32_e32 v65, 31, v64
	v_lshl_add_u64 v[64:65], v[64:65], 0, s[40:41]
	v_lshl_or_b32 v64, v136, 3, v64
	v_lshlrev_b64 v[66:67], 1, v[64:65]
	v_lshl_add_u64 v[64:65], s[24:25], 0, v[66:67]
	s_mov_b64 s[4:5], 0
	s_waitcnt vmcnt(0)
	v_lshlrev_b32_e32 v224, 16, v186
	v_and_b32_e32 v225, 0xffff0000, v186
	v_lshlrev_b32_e32 v226, 16, v187
	v_and_b32_e32 v227, 0xffff0000, v187
	v_pk_mul_f32 v[48:49], v[48:49], v[224:225]
	v_pk_mul_f32 v[50:51], v[50:51], v[226:227]
	v_cvt_pk_bf16_f32 v48, v48, v49
	v_cvt_pk_bf16_f32 v49, v50, v51
	v_lshlrev_b32_e32 v228, 16, v188
	v_and_b32_e32 v229, 0xffff0000, v188
	v_lshlrev_b32_e32 v230, 16, v189
	v_and_b32_e32 v231, 0xffff0000, v189
	v_pk_mul_f32 v[52:53], v[52:53], v[228:229]
	v_pk_mul_f32 v[54:55], v[54:55], v[230:231]
	v_cvt_pk_bf16_f32 v50, v52, v53
	v_cvt_pk_bf16_f32 v51, v54, v55
	s_nop 1
	v_permlane32_swap_b32 v48, v50
	v_permlane32_swap_b32 v49, v51
	global_store_dwordx4 v[64:65], v[48:51], off
	v_lshlrev_b32_e32 v224, 16, v190
	v_and_b32_e32 v225, 0xffff0000, v190
	v_lshlrev_b32_e32 v226, 16, v191
	v_and_b32_e32 v227, 0xffff0000, v191
	v_pk_mul_f32 v[56:57], v[56:57], v[224:225]
	v_pk_mul_f32 v[58:59], v[58:59], v[226:227]
	v_cvt_pk_bf16_f32 v56, v56, v57
	v_cvt_pk_bf16_f32 v57, v58, v59
	v_lshlrev_b32_e32 v228, 16, v192
	v_and_b32_e32 v229, 0xffff0000, v192
	v_lshlrev_b32_e32 v230, 16, v193
	v_and_b32_e32 v231, 0xffff0000, v193
	v_pk_mul_f32 v[60:61], v[60:61], v[228:229]
	v_pk_mul_f32 v[62:63], v[62:63], v[230:231]
	v_cvt_pk_bf16_f32 v58, v60, v61
	v_cvt_pk_bf16_f32 v59, v62, v63
	s_nop 1
	v_permlane32_swap_b32 v56, v58
	v_permlane32_swap_b32 v57, v59
	global_store_dwordx4 v[64:65], v[56:59], off offset:32
	v_lshlrev_b32_e32 v224, 16, v194
	v_and_b32_e32 v225, 0xffff0000, v194
	v_lshlrev_b32_e32 v226, 16, v195
	v_and_b32_e32 v227, 0xffff0000, v195
	v_pk_mul_f32 v[32:33], v[32:33], v[224:225]
	v_pk_mul_f32 v[34:35], v[34:35], v[226:227]
	v_cvt_pk_bf16_f32 v32, v32, v33
	v_cvt_pk_bf16_f32 v33, v34, v35
	v_lshlrev_b32_e32 v228, 16, v196
	v_and_b32_e32 v229, 0xffff0000, v196
	v_lshlrev_b32_e32 v230, 16, v197
	v_and_b32_e32 v231, 0xffff0000, v197
	v_pk_mul_f32 v[36:37], v[36:37], v[228:229]
	v_pk_mul_f32 v[38:39], v[38:39], v[230:231]
	v_cvt_pk_bf16_f32 v34, v36, v37
	v_cvt_pk_bf16_f32 v35, v38, v39
	s_nop 1
	v_permlane32_swap_b32 v32, v34
	v_permlane32_swap_b32 v33, v35
	global_store_dwordx4 v[64:65], v[32:35], off offset:64
	v_lshlrev_b32_e32 v224, 16, v198
	v_and_b32_e32 v225, 0xffff0000, v198
	v_lshlrev_b32_e32 v226, 16, v199
	v_and_b32_e32 v227, 0xffff0000, v199
	v_pk_mul_f32 v[40:41], v[40:41], v[224:225]
	v_pk_mul_f32 v[42:43], v[42:43], v[226:227]
	v_cvt_pk_bf16_f32 v40, v40, v41
	v_cvt_pk_bf16_f32 v41, v42, v43
	v_lshlrev_b32_e32 v228, 16, v200
	v_and_b32_e32 v229, 0xffff0000, v200
	v_lshlrev_b32_e32 v230, 16, v201
	v_and_b32_e32 v231, 0xffff0000, v201
	v_pk_mul_f32 v[44:45], v[44:45], v[228:229]
	v_pk_mul_f32 v[46:47], v[46:47], v[230:231]
	v_cvt_pk_bf16_f32 v42, v44, v45
	v_cvt_pk_bf16_f32 v43, v46, v47
	s_nop 1
	v_permlane32_swap_b32 v40, v42
	v_permlane32_swap_b32 v41, v43
	global_store_dwordx4 v[64:65], v[40:43], off offset:96
	v_lshlrev_b32_e32 v224, 16, v202
	v_and_b32_e32 v225, 0xffff0000, v202
	v_lshlrev_b32_e32 v226, 16, v203
	v_and_b32_e32 v227, 0xffff0000, v203
	v_pk_mul_f32 v[16:17], v[16:17], v[224:225]
	v_pk_mul_f32 v[18:19], v[18:19], v[226:227]
	v_cvt_pk_bf16_f32 v16, v16, v17
	v_cvt_pk_bf16_f32 v17, v18, v19
	v_lshlrev_b32_e32 v228, 16, v204
	v_and_b32_e32 v229, 0xffff0000, v204
	v_lshlrev_b32_e32 v230, 16, v205
	v_and_b32_e32 v231, 0xffff0000, v205
	v_pk_mul_f32 v[20:21], v[20:21], v[228:229]
	v_pk_mul_f32 v[22:23], v[22:23], v[230:231]
	v_cvt_pk_bf16_f32 v18, v20, v21
	v_cvt_pk_bf16_f32 v19, v22, v23
	s_nop 1
	v_permlane32_swap_b32 v16, v18
	v_permlane32_swap_b32 v17, v19
	global_store_dwordx4 v[64:65], v[16:19], off offset:128
	v_lshlrev_b32_e32 v224, 16, v206
	v_and_b32_e32 v225, 0xffff0000, v206
	v_lshlrev_b32_e32 v226, 16, v207
	v_and_b32_e32 v227, 0xffff0000, v207
	v_pk_mul_f32 v[24:25], v[24:25], v[224:225]
	v_pk_mul_f32 v[26:27], v[26:27], v[226:227]
	v_cvt_pk_bf16_f32 v24, v24, v25
	v_cvt_pk_bf16_f32 v25, v26, v27
	v_lshlrev_b32_e32 v228, 16, v208
	v_and_b32_e32 v229, 0xffff0000, v208
	v_lshlrev_b32_e32 v230, 16, v209
	v_and_b32_e32 v231, 0xffff0000, v209
	v_pk_mul_f32 v[28:29], v[28:29], v[228:229]
	v_pk_mul_f32 v[30:31], v[30:31], v[230:231]
	v_cvt_pk_bf16_f32 v26, v28, v29
	v_cvt_pk_bf16_f32 v27, v30, v31
	s_nop 1
	v_permlane32_swap_b32 v24, v26
	v_permlane32_swap_b32 v25, v27
	global_store_dwordx4 v[64:65], v[24:27], off offset:160
	v_lshlrev_b32_e32 v224, 16, v210
	v_and_b32_e32 v225, 0xffff0000, v210
	v_lshlrev_b32_e32 v226, 16, v211
	v_and_b32_e32 v227, 0xffff0000, v211
	v_pk_mul_f32 v[0:1], v[0:1], v[224:225]
	v_pk_mul_f32 v[2:3], v[2:3], v[226:227]
	v_cvt_pk_bf16_f32 v0, v0, v1
	v_cvt_pk_bf16_f32 v1, v2, v3
	v_lshlrev_b32_e32 v228, 16, v212
	v_and_b32_e32 v229, 0xffff0000, v212
	v_lshlrev_b32_e32 v230, 16, v213
	v_and_b32_e32 v231, 0xffff0000, v213
	v_pk_mul_f32 v[4:5], v[4:5], v[228:229]
	v_pk_mul_f32 v[6:7], v[6:7], v[230:231]
	v_cvt_pk_bf16_f32 v2, v4, v5
	v_cvt_pk_bf16_f32 v3, v6, v7
	s_nop 1
	v_permlane32_swap_b32 v0, v2
	v_permlane32_swap_b32 v1, v3
	global_store_dwordx4 v[64:65], v[0:3], off offset:192
	v_lshlrev_b32_e32 v224, 16, v214
	v_and_b32_e32 v225, 0xffff0000, v214
	v_lshlrev_b32_e32 v226, 16, v215
	v_and_b32_e32 v227, 0xffff0000, v215
	v_pk_mul_f32 v[8:9], v[8:9], v[224:225]
	v_pk_mul_f32 v[10:11], v[10:11], v[226:227]
	v_cvt_pk_bf16_f32 v8, v8, v9
	v_cvt_pk_bf16_f32 v9, v10, v11
	v_lshlrev_b32_e32 v228, 16, v220
	v_and_b32_e32 v229, 0xffff0000, v220
	v_lshlrev_b32_e32 v230, 16, v221
	v_and_b32_e32 v231, 0xffff0000, v221
	v_pk_mul_f32 v[12:13], v[12:13], v[228:229]
	v_pk_mul_f32 v[14:15], v[14:15], v[230:231]
	v_cvt_pk_bf16_f32 v10, v12, v13
	v_cvt_pk_bf16_f32 v11, v14, v15
	s_nop 1
	v_permlane32_swap_b32 v8, v10
	v_permlane32_swap_b32 v9, v11
	global_store_dwordx4 v[64:65], v[8:11], off offset:224
	s_waitcnt lgkmcnt(0)
	s_barrier
